# mixer-A PV2 row-sum chain: adjacent scalar add pairs merged into packed adds (17 fewer instructions)
# speedup vs baseline: 1.0045x; 1.0045x over previous
.Lattn_dma_done_a:
	v_exp_f32_e32 v172, v128
	v_exp_f32_e32 v170, v129
	v_exp_f32_e32 v176, v130
	v_exp_f32_e32 v168, v131
	v_exp_f32_e32 v182, v132
	v_exp_f32_e32 v178, v133
	v_exp_f32_e32 v188, v134
	v_exp_f32_e32 v174, v135
	v_exp_f32_e32 v192, v136
	v_exp_f32_e32 v186, v137
	v_exp_f32_e32 v194, v138
	v_exp_f32_e32 v180, v139
	v_exp_f32_e32 v196, v140
	v_exp_f32_e32 v190, v141
	v_exp_f32_e32 v198, v142
	v_exp_f32_e32 v184, v143
	v_cvt_pk_bf16_f32 v144, v173, v169
	v_cvt_pk_bf16_f32 v145, v177, v171
	v_cvt_pk_bf16_f32 v146, v183, v175
	v_cvt_pk_bf16_f32 v147, v189, v179
	v_cvt_pk_bf16_f32 v148, v193, v181
	v_cvt_pk_bf16_f32 v149, v195, v187
	v_cvt_pk_bf16_f32 v150, v197, v185
	v_cvt_pk_bf16_f32 v151, v199, v191
	v_cvt_pk_bf16_f32 v128, v172, v170
	v_cvt_pk_bf16_f32 v129, v176, v168
	v_cvt_pk_bf16_f32 v130, v182, v178
	v_cvt_pk_bf16_f32 v131, v188, v174
	v_cvt_pk_bf16_f32 v132, v192, v186
	v_cvt_pk_bf16_f32 v133, v194, v180
	v_cvt_pk_bf16_f32 v134, v196, v190
	v_cvt_pk_bf16_f32 v135, v198, v184
	v_add3_u32 v160, s7, v162, v160
	v_xad_u32 v252, v163, 64, s7
	v_add_u32_e32 v203, s7, v203
	v_add_u32_e32 v205, s7, v206
	ds_read_b64_tr_b16 v[136:137], v160 offset:32768
	ds_read_b64_tr_b16 v[138:139], v160 offset:34816
	ds_read_b64_tr_b16 v[140:141], v160 offset:36864
	ds_read_b64_tr_b16 v[142:143], v160 offset:38912
	ds_read_b64_tr_b16 v[152:153], v252 offset:32768
	ds_read_b64_tr_b16 v[154:155], v252 offset:34816
	ds_read_b64_tr_b16 v[156:157], v252 offset:36864
	ds_read_b64_tr_b16 v[158:159], v252 offset:38912
	ds_read_b64_tr_b16 v[208:209], v203 offset:32768
	ds_read_b64_tr_b16 v[210:211], v203 offset:34816
	ds_read_b64_tr_b16 v[212:213], v203 offset:36864
	ds_read_b64_tr_b16 v[214:215], v203 offset:38912
	ds_read_b64_tr_b16 v[216:217], v205 offset:32768
	ds_read_b64_tr_b16 v[218:219], v205 offset:34816
	ds_read_b64_tr_b16 v[220:221], v205 offset:36864
	ds_read_b64_tr_b16 v[222:223], v205 offset:38912
	s_waitcnt lgkmcnt(14)
	v_mfma_f32_32x32x16_bf16 v[64:79], v[144:147], v[136:139], v[64:79]
	v_mfma_f32_32x32x16_bf16 v[0:15], v[128:131], v[136:139], v[0:15]
	s_waitcnt lgkmcnt(10)
	v_mfma_f32_32x32x16_bf16 v[80:95], v[144:147], v[152:155], v[80:95]
	v_mfma_f32_32x32x16_bf16 v[16:31], v[128:131], v[152:155], v[16:31]
	s_waitcnt lgkmcnt(6)
	v_mfma_f32_32x32x16_bf16 v[96:111], v[144:147], v[208:211], v[96:111]
	v_mfma_f32_32x32x16_bf16 v[32:47], v[128:131], v[208:211], v[32:47]
	s_waitcnt lgkmcnt(2)
	v_mfma_f32_32x32x16_bf16 v[112:127], v[144:147], v[216:219], v[112:127]
	v_mfma_f32_32x32x16_bf16 v[48:63], v[128:131], v[216:219], v[48:63]
	v_mfma_f32_32x32x16_bf16 v[64:79], v[148:151], v[140:143], v[64:79]
	v_mfma_f32_32x32x16_bf16 v[0:15], v[132:135], v[140:143], v[0:15]
	v_mfma_f32_32x32x16_bf16 v[80:95], v[148:151], v[156:159], v[80:95]
	v_mfma_f32_32x32x16_bf16 v[16:31], v[132:135], v[156:159], v[16:31]
	v_mfma_f32_32x32x16_bf16 v[96:111], v[148:151], v[212:215], v[96:111]
	v_mfma_f32_32x32x16_bf16 v[32:47], v[132:135], v[212:215], v[32:47]
	s_waitcnt lgkmcnt(0)
	v_mfma_f32_32x32x16_bf16 v[112:127], v[148:151], v[220:223], v[112:127]
	v_mfma_f32_32x32x16_bf16 v[48:63], v[132:135], v[220:223], v[48:63]
	ds_read_b128 v[128:131], v207 offset:4096
	ds_read_b128 v[132:135], v224
	ds_read_b128 v[136:139], v225 offset:4096
	ds_read_b128 v[140:143], v226
	s_waitcnt lgkmcnt(2)
	v_mfma_f32_32x32x16_bf16 v[144:159], v[128:131], v[132:135], 0
	ds_read_b128 v[128:131], v227 offset:4096
	ds_read_b128 v[132:135], v228
	s_waitcnt lgkmcnt(2)
	v_mfma_f32_32x32x16_bf16 v[144:159], v[136:139], v[140:143], v[144:159]
	ds_read_b128 v[136:139], v230 offset:4096
	ds_read_b128 v[140:143], v232
	s_waitcnt lgkmcnt(2)
	v_mfma_f32_32x32x16_bf16 v[144:159], v[128:131], v[132:135], v[144:159]
	ds_read_b128 v[128:131], v207 offset:12288
	ds_read_b128 v[132:135], v224 offset:4096
	s_waitcnt lgkmcnt(2)
	v_mfma_f32_32x32x16_bf16 v[144:159], v[136:139], v[140:143], v[144:159]
	ds_read_b128 v[208:211], v225 offset:12288
	ds_read_b128 v[212:215], v226 offset:4096
	s_waitcnt lgkmcnt(2)
	v_mfma_f32_32x32x16_bf16 v[128:143], v[128:131], v[132:135], 0
	s_nop 7
	v_exp_f32_e32 v229, v144
	v_exp_f32_e32 v145, v145
	v_exp_f32_e32 v231, v146
	v_exp_f32_e32 v147, v147
	ds_read_b128 v[216:219], v227 offset:12288
	ds_read_b128 v[220:223], v228 offset:4096
	s_waitcnt lgkmcnt(2)
	v_mfma_f32_32x32x16_bf16 v[128:143], v[208:211], v[212:215], v[128:143]
	v_exp_f32_e32 v233, v148
	v_exp_f32_e32 v235, v149
	v_exp_f32_e32 v237, v150
	v_exp_f32_e32 v239, v151
	ds_read_b128 v[148:151], v230 offset:12288
	ds_read_b128 v[208:211], v232 offset:4096
	s_waitcnt lgkmcnt(2)
	v_mfma_f32_32x32x16_bf16 v[128:143], v[216:219], v[220:223], v[128:143]
	v_exp_f32_e32 v241, v152
	v_exp_f32_e32 v243, v153
	v_exp_f32_e32 v245, v154
	v_exp_f32_e32 v247, v155
	s_waitcnt lgkmcnt(0)
	v_mfma_f32_32x32x16_bf16 v[128:143], v[148:151], v[208:211], v[128:143]
	v_exp_f32_e32 v249, v156
	v_exp_f32_e32 v251, v157
	v_exp_f32_e32 v207, v158
	v_exp_f32_e32 v163, v159
	s_nop 7
	v_exp_f32_e32 v228, v128
	v_exp_f32_e32 v146, v129
	v_exp_f32_e32 v230, v130
	v_exp_f32_e32 v144, v131
	v_exp_f32_e32 v232, v132
	v_exp_f32_e32 v238, v133
	v_exp_f32_e32 v236, v134
	v_exp_f32_e32 v234, v135
	v_exp_f32_e32 v240, v136
	v_exp_f32_e32 v246, v137
	v_exp_f32_e32 v244, v138
	v_exp_f32_e32 v242, v139
	v_exp_f32_e32 v248, v140
	v_exp_f32_e32 v162, v141
	v_exp_f32_e32 v206, v142
	v_exp_f32_e32 v250, v143
	v_cvt_pk_bf16_f32 v148, v229, v145
	v_cvt_pk_bf16_f32 v149, v231, v147
	v_cvt_pk_bf16_f32 v150, v233, v235
	v_cvt_pk_bf16_f32 v151, v237, v239
	v_cvt_pk_bf16_f32 v152, v241, v243
	v_cvt_pk_bf16_f32 v153, v245, v247
	v_cvt_pk_bf16_f32 v154, v249, v251
	v_cvt_pk_bf16_f32 v155, v207, v163
	v_cvt_pk_bf16_f32 v128, v228, v146
	v_cvt_pk_bf16_f32 v129, v230, v144
	v_cvt_pk_bf16_f32 v130, v232, v238
	v_cvt_pk_bf16_f32 v131, v236, v234
	v_cvt_pk_bf16_f32 v132, v240, v246
	v_cvt_pk_bf16_f32 v133, v244, v242
	v_cvt_pk_bf16_f32 v134, v248, v162
	v_cvt_pk_bf16_f32 v135, v206, v250
	s_addk_i32 s5, 0x4000
	s_add_i32 s4, s4, 0x10000
	s_and_b32 s7, s5, 0x4000
	ds_read_b64_tr_b16 v[136:137], v160 offset:40960
	ds_read_b64_tr_b16 v[138:139], v160 offset:43008
	ds_read_b64_tr_b16 v[140:141], v160 offset:45056
	ds_read_b64_tr_b16 v[142:143], v160 offset:47104
	ds_read_b64_tr_b16 v[156:157], v252 offset:40960
	ds_read_b64_tr_b16 v[158:159], v252 offset:43008
	ds_read_b64_tr_b16 v[208:209], v252 offset:45056
	ds_read_b64_tr_b16 v[210:211], v252 offset:47104
	ds_read_b64_tr_b16 v[212:213], v203 offset:40960
	ds_read_b64_tr_b16 v[214:215], v203 offset:43008
	ds_read_b64_tr_b16 v[216:217], v203 offset:45056
	ds_read_b64_tr_b16 v[218:219], v203 offset:47104
	ds_read_b64_tr_b16 v[220:221], v205 offset:40960
	ds_read_b64_tr_b16 v[222:223], v205 offset:43008
	ds_read_b64_tr_b16 v[224:225], v205 offset:45056
	ds_read_b64_tr_b16 v[226:227], v205 offset:47104
	s_waitcnt lgkmcnt(14)
	v_mfma_f32_32x32x16_bf16 v[64:79], v[148:151], v[136:139], v[64:79]
	v_mfma_f32_32x32x16_bf16 v[0:15], v[128:131], v[136:139], v[0:15]
	s_waitcnt lgkmcnt(10)
	v_mfma_f32_32x32x16_bf16 v[80:95], v[148:151], v[156:159], v[80:95]
	v_mfma_f32_32x32x16_bf16 v[16:31], v[128:131], v[156:159], v[16:31]
	s_waitcnt lgkmcnt(6)
	v_mfma_f32_32x32x16_bf16 v[96:111], v[148:151], v[212:215], v[96:111]
	v_mfma_f32_32x32x16_bf16 v[32:47], v[128:131], v[212:215], v[32:47]
	s_waitcnt lgkmcnt(2)
	v_mfma_f32_32x32x16_bf16 v[112:127], v[148:151], v[220:223], v[112:127]
	v_mfma_f32_32x32x16_bf16 v[48:63], v[128:131], v[220:223], v[48:63]
	v_pk_add_f32 v[128:129], v[172:173], v[176:177]
	v_pk_add_f32 v[130:131], v[168:169], v[170:171]
	v_pk_add_f32 v[136:137], v[182:183], v[188:189]
	v_pk_add_f32 v[128:129], v[136:137], v[128:129]
	v_pk_add_f32 v[136:137], v[174:175], v[178:179]
	v_pk_add_f32 v[138:139], v[232:233], v[236:237]
	v_pk_add_f32 v[130:131], v[136:137], v[130:131]
	v_pk_add_f32 v[136:137], v[192:193], v[194:195]
	v_mfma_f32_32x32x16_bf16 v[64:79], v[152:155], v[140:143], v[64:79]
	v_pk_add_f32 v[128:129], v[136:137], v[128:129]
	v_pk_add_f32 v[136:137], v[180:181], v[186:187]
	v_pk_add_f32 v[130:131], v[136:137], v[130:131]
	v_pk_add_f32 v[136:137], v[196:197], v[198:199]
	s_nop 0
	v_pk_add_f32 v[128:129], v[136:137], v[128:129]
	v_pk_add_f32 v[136:137], v[184:185], v[190:191]
	v_mfma_f32_32x32x16_bf16 v[0:15], v[132:135], v[140:143], v[0:15]
	v_pk_add_f32 v[130:131], v[136:137], v[130:131]
	v_pk_add_f32 v[136:137], v[144:145], v[146:147]
	v_pk_add_f32 v[128:129], v[128:129], v[130:131]
	v_pk_add_f32 v[130:131], v[228:229], v[230:231]
	v_pk_add_f32 v[128:129], v[166:167], v[128:129]
	v_mfma_f32_32x32x16_bf16 v[80:95], v[152:155], v[208:211], v[80:95]
	v_pk_add_f32 v[130:131], v[138:139], v[130:131]
	v_pk_add_f32 v[138:139], v[234:235], v[238:239]
	v_pk_add_f32 v[136:137], v[138:139], v[136:137]
	v_pk_add_f32 v[138:139], v[240:241], v[244:245]
	s_nop 0
	v_pk_add_f32 v[130:131], v[138:139], v[130:131]
	v_mfma_f32_32x32x16_bf16 v[16:31], v[132:135], v[208:211], v[16:31]
	v_pk_add_f32 v[138:139], v[242:243], v[246:247]
	v_pk_add_f32 v[136:137], v[138:139], v[136:137]
	v_pk_add_f32 v[138:139], v[248:249], v[206:207]
	v_pk_add_f32 v[130:131], v[138:139], v[130:131]
	v_pk_add_f32 v[138:139], v[250:251], v[162:163]
	v_mfma_f32_32x32x16_bf16 v[96:111], v[152:155], v[216:219], v[96:111]
	v_pk_add_f32 v[136:137], v[138:139], v[136:137]
	v_pk_add_f32 v[130:131], v[130:131], v[136:137]
	v_pk_add_f32 v[166:167], v[128:129], v[130:131]
	v_mfma_f32_32x32x16_bf16 v[32:47], v[132:135], v[216:219], v[32:47]
	s_waitcnt lgkmcnt(0)
	v_mfma_f32_32x32x16_bf16 v[112:127], v[152:155], v[224:227], v[112:127]
	v_mfma_f32_32x32x16_bf16 v[48:63], v[132:135], v[224:227], v[48:63]
	s_waitcnt vmcnt(0)
	s_cmp_eq_u32 s4, 0x400000
	s_cbranch_scc0 .Lattn_head_a
	s_barrier
